# attn8: split ds_read2_b64 V reads into two ds_read_b64 (bank conflicts)
# speedup vs baseline: 1.0090x; 1.0090x over previous
.LBB0_929:
	s_add_i32 s4, s7, 1
	s_min_i32 s20, s4, s6
	v_lshlrev_b64 v[66:67], v108, s[20:21]
	v_lshlrev_b64 v[148:149], v110, s[20:21]
	v_mul_hi_u32_u24_e32 v161, s20, v100
	v_mul_u32_u24_e32 v160, s20, v100
	s_lshl_b32 s20, s20, 8
	s_bitcmp1_b32 s7, 0
	s_cselect_b32 s5, 0xac00, 0
	v_or_b32_e32 v28, s5, v86
	v_add_u32_e32 v53, v28, v105
	ds_read_b128 v[28:31], v53
	ds_read_b128 v[32:35], v53 offset:64
	ds_read_b128 v[36:39], v53 offset:3328
	ds_read_b128 v[120:123], v53 offset:128
	ds_read_b128 v[40:43], v53 offset:6656
	ds_read_b128 v[44:47], v53 offset:6720
	ds_read_b128 v[48:51], v53 offset:9984
	ds_read_b128 v[80:83], v53 offset:6784
	s_waitcnt lgkmcnt(1)
	v_mfma_f32_16x16x32_bf16 v[54:57], v[48:51], v[0:3], 0
	ds_read_b128 v[48:51], v53 offset:13312
	ds_read_b128 v[58:61], v53 offset:13376
	v_mov_b32_e32 v119, v52
	s_waitcnt lgkmcnt(1)
	v_mfma_f32_16x16x32_bf16 v[62:65], v[48:51], v[0:3], 0
	ds_read_b128 v[48:51], v53 offset:16640
	ds_read_b128 v[72:75], v53 offset:13440
	v_mfma_f32_16x16x32_bf16 v[28:31], v[28:31], v[0:3], 0
	s_waitcnt lgkmcnt(1)
	v_mfma_f32_16x16x32_bf16 v[68:71], v[48:51], v[0:3], 0
	ds_read_b128 v[48:51], v53 offset:19968
	ds_read_b128 v[124:127], v53 offset:20032
	v_mfma_f32_16x16x32_bf16 v[36:39], v[36:39], v[0:3], 0
	s_waitcnt lgkmcnt(1)
	v_mfma_f32_16x16x32_bf16 v[128:131], v[48:51], v[0:3], 0
	ds_read_b128 v[76:79], v53 offset:23296
	ds_read_b128 v[48:51], v53 offset:20096
	v_mfma_f32_16x16x32_bf16 v[136:139], v[32:35], v[4:7], v[28:31]
	s_nop 2
	ds_read_b128 v[28:31], v53 offset:3392
	ds_read_b128 v[140:143], v53 offset:3456
	v_lshl_add_u64 v[32:33], v[66:67], 1, v[92:93]
	v_lshl_add_u64 v[34:35], v[148:149], 1, v[94:95]
	s_waitcnt lgkmcnt(1)
	v_mfma_f32_16x16x32_bf16 v[144:147], v[28:31], v[4:7], v[36:39]
	ds_read_b128 v[28:31], v53 offset:10048
	ds_read_b128 v[152:155], v53 offset:10112
	v_mfma_f32_16x16x32_bf16 v[40:43], v[40:43], v[0:3], 0
	v_mfma_f32_16x16x32_bf16 v[132:135], v[76:79], v[0:3], 0
	s_waitcnt lgkmcnt(1)
	v_mfma_f32_16x16x32_bf16 v[156:159], v[28:31], v[4:7], v[54:57]
	v_mfma_f32_16x16x32_bf16 v[76:79], v[58:61], v[4:7], v[62:65]
	ds_read_b128 v[28:31], v53 offset:16704
	s_nop 1
	ds_read_b128 v[64:67], v53 offset:16768
	v_mfma_f32_16x16x32_bf16 v[148:151], v[44:47], v[4:7], v[40:43]
	v_lshl_add_u64 v[44:45], v[106:107], 0, s[20:21]
	v_lshl_add_u64 v[46:47], v[112:113], 0, s[20:21]
	s_nop 0
	v_lshl_add_u64 v[40:41], v[160:161], 1, v[96:97]
	s_waitcnt lgkmcnt(1)
	v_mfma_f32_16x16x32_bf16 v[68:71], v[28:31], v[4:7], v[68:71]
	global_load_dwordx4 v[36:39], v[32:33], off
	s_nop 0
	global_load_dwordx4 v[32:35], v[34:35], off
	s_nop 0
	global_load_dwordx4 v[28:31], v[40:41], off
	ds_read_b128 v[40:43], v53 offset:23360
	ds_read_b128 v[52:55], v53 offset:23424
	s_waitcnt lgkmcnt(1)
	v_mfma_f32_16x16x32_bf16 v[56:59], v[40:43], v[4:7], v[132:135]
	global_load_dwordx4 v[40:43], v[44:45], off
	s_nop 0
	global_load_dwordx4 v[44:47], v[46:47], off
	v_mfma_f32_16x16x32_bf16 v[120:123], v[120:123], v[8:11], v[136:139]
	v_mfma_f32_16x16x32_bf16 v[60:63], v[124:127], v[4:7], v[128:131]
	v_or_b32_e32 v124, s5, v102
	s_nop 1
	v_add_u32_e32 v128, v124, v111
	v_mfma_f32_16x16x32_bf16 v[124:127], v[140:143], v[8:11], v[144:147]
	v_add_u32_e32 v172, 0x6800, v128
	v_add_u32_e32 v176, 0x7800, v128
	v_add_u32_e32 v177, 0x8800, v128
	s_waitcnt lgkmcnt(0)
	v_mfma_f32_16x16x32_bf16 v[52:55], v[52:55], v[8:11], v[56:59]
	v_add_u32_e32 v180, 0x9800, v128
	ds_read_b64 v[128:129], v172
	ds_read_b64 v[130:131], v172 offset:32
	ds_read_b64 v[132:133], v176 offset:256
	ds_read_b64 v[134:135], v176 offset:288
	ds_read_b64 v[136:137], v177 offset:512
	ds_read_b64 v[138:139], v177 offset:544
	ds_read_b64 v[140:141], v180 offset:768
	ds_read_b64 v[142:143], v180 offset:800
	v_max_f32_e32 v56, v121, v121
	v_max_f32_e32 v57, v120, v120
	v_mfma_f32_16x16x32_bf16 v[80:83], v[80:83], v[8:11], v[148:151]
	v_max_f32_e32 v56, v57, v56
	v_max3_f32 v56, v56, v122, v123
	v_max3_f32 v56, v56, v124, v125
	v_mfma_f32_16x16x32_bf16 v[144:147], v[152:155], v[8:11], v[156:159]
	v_max3_f32 v56, v56, v126, v127
	s_nop 2
	v_max3_f32 v56, v56, v80, v81
	v_max3_f32 v56, v56, v82, v83
	v_mfma_f32_16x16x32_bf16 v[72:75], v[72:75], v[8:11], v[76:79]
	ds_read_b64 v[148:149], v172 offset:64
	ds_read_b64 v[150:151], v172 offset:96
	ds_read_b64 v[152:153], v176 offset:320
	ds_read_b64 v[154:155], v176 offset:352
	ds_read_b64 v[156:157], v177 offset:576
	ds_read_b64 v[158:159], v177 offset:608
	v_max3_f32 v56, v56, v144, v145
	v_max3_f32 v56, v56, v146, v147
	v_mfma_f32_16x16x32_bf16 v[64:67], v[64:67], v[8:11], v[68:71]
	s_nop 1
	v_max3_f32 v56, v56, v72, v73
	v_max3_f32 v56, v56, v74, v75
	ds_read_b64 v[76:77], v180 offset:832
	ds_read_b64 v[78:79], v180 offset:864
	ds_read_b64 v[160:161], v172 offset:128
	ds_read_b64 v[162:163], v172 offset:160
	ds_read_b64 v[164:165], v176 offset:384
	ds_read_b64 v[166:167], v176 offset:416
	v_mfma_f32_16x16x32_bf16 v[48:51], v[48:51], v[8:11], v[60:63]
	v_max3_f32 v56, v56, v64, v65
	v_max3_f32 v56, v56, v66, v67
	ds_read_b64 v[68:69], v177 offset:640
	ds_read_b64 v[70:71], v177 offset:672
	ds_read_b64 v[168:169], v180 offset:896
	ds_read_b64 v[170:171], v180 offset:928
	ds_read_b64 v[174:175], v172 offset:224
	ds_read_b64 v[172:173], v172 offset:192
	s_nop 2
	v_max3_f32 v56, v56, v48, v49
	v_max3_f32 v56, v56, v50, v51
	v_max3_f32 v56, v56, v52, v53
	v_max3_f32 v56, v56, v54, v55
	v_mov_b32_e32 v57, v56
	s_nop 1
	v_permlane16_swap_b32_e32 v56, v57
	v_max_f32_e32 v57, v57, v57
	v_max_f32_e32 v56, v56, v56
	v_max_f32_e32 v56, v56, v57
	v_mov_b32_e32 v57, v56
	s_nop 1
	v_permlane32_swap_b32_e32 v56, v57
	v_max3_f32 v184, v118, v56, v57
	v_sub_f32_e32 v118, v118, v184
	v_sub_f32_e32 v56, v120, v184
	v_sub_f32_e32 v57, v124, v184
	v_sub_f32_e32 v58, v121, v184
	v_sub_f32_e32 v59, v125, v184
	v_sub_f32_e32 v120, v122, v184
	v_sub_f32_e32 v121, v126, v184
	v_sub_f32_e32 v122, v123, v184
	v_sub_f32_e32 v123, v127, v184
	v_sub_f32_e32 v125, v145, v184
	v_sub_f32_e32 v127, v147, v184
	v_sub_f32_e32 v145, v64, v184
	v_sub_f32_e32 v147, v65, v184
	v_sub_f32_e32 v186, v66, v184
	v_sub_f32_e32 v188, v67, v184
	v_exp_f32_e32 v56, v56
	v_exp_f32_e32 v57, v57
	v_exp_f32_e32 v58, v58
	v_exp_f32_e32 v59, v59
	v_exp_f32_e32 v64, v120
	v_exp_f32_e32 v65, v121
	v_exp_f32_e32 v66, v122
	v_exp_f32_e32 v67, v123
	v_exp_f32_e32 v118, v118
	v_sub_f32_e32 v80, v80, v184
	v_sub_f32_e32 v124, v144, v184
	v_sub_f32_e32 v81, v81, v184
	v_sub_f32_e32 v82, v82, v184
	v_sub_f32_e32 v126, v146, v184
	v_sub_f32_e32 v83, v83, v184
	v_sub_f32_e32 v144, v72, v184
	v_sub_f32_e32 v146, v73, v184
	v_sub_f32_e32 v185, v74, v184
	v_sub_f32_e32 v187, v75, v184
	v_sub_f32_e32 v189, v48, v184
	v_sub_f32_e32 v191, v49, v184
	v_sub_f32_e32 v193, v50, v184
	v_sub_f32_e32 v195, v51, v184
	v_exp_f32_e32 v72, v80
	v_exp_f32_e32 v73, v124
	v_exp_f32_e32 v74, v81
	v_exp_f32_e32 v75, v125
	v_exp_f32_e32 v80, v82
	v_exp_f32_e32 v81, v126
	v_exp_f32_e32 v82, v83
	v_exp_f32_e32 v83, v127
	v_pk_mul_f32 v[26:27], v[26:27], v[118:119] op_sel_hi:[1,0]
	v_pk_mul_f32 v[24:25], v[24:25], v[118:119] op_sel_hi:[1,0]
	v_cvt_pk_bf16_f32 v48, v56, v58
	v_cvt_pk_bf16_f32 v49, v64, v66
	v_cvt_pk_bf16_f32 v50, v57, v59
	v_cvt_pk_bf16_f32 v51, v65, v67
	v_pk_mul_f32 v[22:23], v[22:23], v[118:119] op_sel_hi:[1,0]
	v_pk_mul_f32 v[20:21], v[20:21], v[118:119] op_sel_hi:[1,0]
	v_pk_mul_f32 v[18:19], v[18:19], v[118:119] op_sel_hi:[1,0]
	v_pk_mul_f32 v[16:17], v[16:17], v[118:119] op_sel_hi:[1,0]
	v_pk_mul_f32 v[14:15], v[14:15], v[118:119] op_sel_hi:[1,0]
	v_pk_mul_f32 v[12:13], v[12:13], v[118:119] op_sel_hi:[1,0]
	s_waitcnt lgkmcnt(15)
	v_mfma_f32_16x16x32_bf16 v[24:27], v[128:131], v[48:51], v[24:27]
	v_sub_f32_e32 v190, v52, v184
	v_sub_f32_e32 v192, v53, v184
	v_sub_f32_e32 v194, v54, v184
	s_waitcnt lgkmcnt(15)
	v_mfma_f32_16x16x32_bf16 v[20:23], v[132:135], v[48:51], v[20:23]
	v_sub_f32_e32 v196, v55, v184
	v_exp_f32_e32 v120, v144
	v_exp_f32_e32 v121, v145
	s_waitcnt lgkmcnt(15)
	v_mfma_f32_16x16x32_bf16 v[16:19], v[136:139], v[48:51], v[16:19]
	v_exp_f32_e32 v122, v146
	v_exp_f32_e32 v123, v147
	v_exp_f32_e32 v124, v185
	s_waitcnt lgkmcnt(15)
	v_mfma_f32_16x16x32_bf16 v[12:15], v[140:143], v[48:51], v[12:15]
	v_cvt_pk_bf16_f32 v52, v72, v74
	v_cvt_pk_bf16_f32 v53, v80, v82
	v_cvt_pk_bf16_f32 v54, v73, v75
	v_cvt_pk_bf16_f32 v55, v81, v83
	v_exp_f32_e32 v125, v186
	v_exp_f32_e32 v126, v187
	v_exp_f32_e32 v127, v188
	s_waitcnt lgkmcnt(15)
	v_mfma_f32_16x16x32_bf16 v[24:27], v[148:151], v[52:55], v[24:27]
	v_add_f32_e64 v56, v56, 0
	v_add_f32_e64 v57, v57, 0
	v_cvt_pk_bf16_f32 v48, v120, v122
	v_cvt_pk_bf16_f32 v49, v124, v126
	s_waitcnt lgkmcnt(14)
	v_mfma_f32_16x16x32_bf16 v[20:23], v[152:155], v[52:55], v[20:23]
	v_cvt_pk_bf16_f32 v50, v121, v123
	v_cvt_pk_bf16_f32 v51, v125, v127
	v_pk_add_f32 v[56:57], v[58:59], v[56:57]
	s_waitcnt lgkmcnt(12)
	v_mfma_f32_16x16x32_bf16 v[16:19], v[156:159], v[52:55], v[16:19]
	v_exp_f32_e32 v128, v189
	v_exp_f32_e32 v129, v190
	ds_read_b64 v[60:61], v176 offset:448
	ds_read_b64 v[62:63], v176 offset:480
	ds_read_b64 v[178:179], v177 offset:736
	ds_read_b64 v[176:177], v177 offset:704
	ds_read_b64 v[182:183], v180 offset:992
	ds_read_b64 v[180:181], v180 offset:960
	s_waitcnt lgkmcnt(15)
	v_mfma_f32_16x16x32_bf16 v[12:15], v[76:79], v[52:55], v[12:15]
	v_exp_f32_e32 v130, v191
	v_exp_f32_e32 v131, v192
	v_exp_f32_e32 v132, v193
	s_waitcnt lgkmcnt(14)
	v_mfma_f32_16x16x32_bf16 v[24:27], v[160:163], v[48:51], v[24:27]
	v_exp_f32_e32 v133, v194
	v_exp_f32_e32 v76, v195
	v_exp_f32_e32 v77, v196
	s_waitcnt lgkmcnt(12)
	v_mfma_f32_16x16x32_bf16 v[20:23], v[164:167], v[48:51], v[20:23]
	v_cvt_pk_bf16_f32 v52, v128, v130
	v_cvt_pk_bf16_f32 v53, v132, v76
	v_cvt_pk_bf16_f32 v54, v129, v131
	s_waitcnt lgkmcnt(10)
	v_mfma_f32_16x16x32_bf16 v[16:19], v[68:71], v[48:51], v[16:19]
	v_cvt_pk_bf16_f32 v55, v133, v77
	s_waitcnt lgkmcnt(8)
	v_mfma_f32_16x16x32_bf16 v[12:15], v[168:171], v[48:51], v[12:15]
	v_add_f32_e64 v48, v64, v56
	v_add_f32_e64 v49, v65, v57
	v_pk_add_f32 v[48:49], v[66:67], v[48:49]
	s_waitcnt lgkmcnt(6)
	v_mfma_f32_16x16x32_bf16 v[24:27], v[172:175], v[52:55], v[24:27]
	v_add_f32_e64 v48, v72, v48
	v_add_f32_e64 v49, v73, v49
	v_pk_add_f32 v[48:49], v[74:75], v[48:49]
	s_waitcnt lgkmcnt(4)
	v_mfma_f32_16x16x32_bf16 v[20:23], v[60:63], v[52:55], v[20:23]
	v_add_f32_e64 v48, v80, v48
	v_add_f32_e64 v49, v81, v49
	v_pk_add_f32 v[48:49], v[82:83], v[48:49]
	s_waitcnt lgkmcnt(2)
	v_mfma_f32_16x16x32_bf16 v[16:19], v[176:179], v[52:55], v[16:19]
	v_add_f32_e64 v48, v120, v48
	v_add_f32_e64 v49, v121, v49
	v_pk_add_f32 v[48:49], v[122:123], v[48:49]
	s_waitcnt lgkmcnt(0)
	v_mfma_f32_16x16x32_bf16 v[12:15], v[180:183], v[52:55], v[12:15]
	v_add_f32_e64 v48, v124, v48
	v_add_f32_e64 v49, v125, v49
	v_pk_add_f32 v[48:49], v[126:127], v[48:49]
	s_nop 0
	v_pk_add_f32 v[48:49], v[128:129], v[48:49]
	s_nop 0
	v_pk_add_f32 v[48:49], v[130:131], v[48:49]
	s_nop 0
	v_pk_add_f32 v[48:49], v[132:133], v[48:49]
	s_nop 0
	v_pk_add_f32 v[48:49], v[76:77], v[48:49]
	s_nop 0
	v_add_f32_e32 v52, v48, v49
	v_fmac_f32_e32 v52, v119, v118
	s_bitcmp1_b32 s4, 0
	s_cselect_b32 s5, 0xac00, 0
	v_add3_u32 v48, s5, v114, v101
	s_waitcnt vmcnt(4)
	ds_write_b128 v48, v[36:39]
	v_add3_u32 v36, s5, v115, v103
	s_waitcnt vmcnt(3)
	ds_write_b128 v36, v[32:35]
	v_add3_u32 v32, s5, v116, v99
	s_waitcnt vmcnt(2)
	ds_write_b128 v32, v[28:31]
	v_add3_u32 v28, s5, v117, v104
	s_cmp_lg_u32 s33, s4
	v_mov_b32_e32 v118, v184
	s_mov_b32 s7, s4
	s_waitcnt vmcnt(1)
	ds_write_b128 v28, v[40:43] offset:26624
	s_waitcnt vmcnt(0)
	ds_write_b128 v28, v[44:47] offset:35328
	s_waitcnt lgkmcnt(0)
	s_barrier
	s_cbranch_scc1 .LBB0_929
	v_mov_b32_e32 v0, v52
	s_nop 1
	v_permlane16_swap_b32_e32 v52, v0
	v_add_f32_e32 v0, v52, v0
	v_mov_b32_e32 v1, v0
	s_nop 1
	v_permlane32_swap_b32_e32 v0, v1
	v_add_f32_e32 v0, v0, v1
	v_div_scale_f32 v1, s[4:5], v0, v0, 1.0
	v_rcp_f32_e32 v2, v1
	v_mov_b32_e32 v99, v87
	v_lshlrev_b64 v[8:9], 1, v[98:99]
	v_mov_b32_e32 v103, v87
	v_fma_f32 v3, -v1, v2, 1.0
	v_fmac_f32_e32 v2, v3, v2
	v_div_scale_f32 v3, vcc, 1.0, v0, 1.0
	v_mul_f32_e32 v4, v3, v2
	v_fma_f32 v5, -v1, v4, v3
	v_fmac_f32_e32 v4, v5, v2
	v_fma_f32 v1, -v1, v4, v3
	v_div_fmas_f32 v1, v1, v2, v4
	v_div_fixup_f32 v0, v1, v0, 1.0
	v_lshlrev_b64 v[2:3], 11, v[90:91]
	v_pk_mul_f32 v[4:5], v[24:25], v[0:1] op_sel_hi:[1,0]
	v_pk_mul_f32 v[6:7], v[26:27], v[0:1] op_sel_hi:[1,0]
	v_cvt_pk_bf16_f32 v4, v4, v5
	v_cvt_pk_bf16_f32 v5, v6, v7
	v_lshl_add_u64 v[6:7], s[16:17], 0, v[2:3]
	v_lshl_add_u64 v[2:3], s[34:35], 0, v[2:3]
	v_lshl_add_u64 v[6:7], v[6:7], 0, v[8:9]
	v_lshl_add_u64 v[2:3], v[2:3], 0, v[8:9]
	v_lshl_add_u64 v[6:7], v[6:7], 0, v[102:103]
	v_lshl_add_u64 v[2:3], v[2:3], 0, v[102:103]
	global_store_dwordx2 v[6:7], v[4:5], off
	v_pk_mul_f32 v[4:5], v[20:21], v[0:1] op_sel_hi:[1,0]
	v_pk_mul_f32 v[6:7], v[22:23], v[0:1] op_sel_hi:[1,0]
	v_add_co_u32_e32 v2, vcc, s30, v2
	v_cvt_pk_bf16_f32 v4, v4, v5
	v_cvt_pk_bf16_f32 v5, v6, v7
	v_addc_co_u32_e32 v3, vcc, 0, v3, vcc
	global_store_dwordx2 v[2:3], v[4:5], off offset:32
	v_pk_mul_f32 v[4:5], v[16:17], v[0:1] op_sel_hi:[1,0]
	v_pk_mul_f32 v[6:7], v[18:19], v[0:1] op_sel_hi:[1,0]
	v_cvt_pk_bf16_f32 v4, v4, v5
	v_cvt_pk_bf16_f32 v5, v6, v7
	global_store_dwordx2 v[2:3], v[4:5], off offset:64
	v_pk_mul_f32 v[4:5], v[12:13], v[0:1] op_sel_hi:[1,0]
	v_pk_mul_f32 v[0:1], v[14:15], v[0:1] op_sel_hi:[1,0]
	v_cvt_pk_bf16_f32 v4, v4, v5
	v_cvt_pk_bf16_f32 v5, v0, v1
	global_store_dwordx2 v[2:3], v[4:5], off offset:96
	s_load_dword s6, s[18:19], 0x0
	s_waitcnt lgkmcnt(0)
	s_add_i32 s31, s6, s31
	s_cmpk_gt_i32 s31, 0x1ff
	s_cbranch_scc0 .LBB0_912
